# mixer-C key tile staged by LDS-DMA as 8 rows x 128 B per instruction (swizzled LDS image, conflict-free fragment reads) instead of a 64-row 16-byte gather
# speedup vs baseline: 1.0103x; 1.0053x over previous
; template <int DQK, int MODE> __device__ __forceinline__ void unit(const Desc& d, int q0, ATT_LAS char* shm, const float* biasg, float sinkl2) {
;     ...
;     ATT_DMA(t0, 0);
.LBB0_555:
	v_mov_b32_e32 v4, v228
	s_nop 0
	v_readfirstlane_b32 s36, v4
	s_ashr_i32 s50, s36, 6
	s_cmp_lt_i32 s50, 12
	s_cselect_b64 s[30:31], -1, 0
	s_cmp_gt_i32 s50, 11
	v_and_b32_e32 v214, 63, v4
	v_and_b32_e32 v236, 7, v214
	v_bfe_u32 v242, v214, 4, 2
	v_xor_b32_e32 v236, v236, v242
	v_mov_b32_e32 v243, s50
	v_bfe_u32 v242, v243, 1, 1
	v_lshlrev_b32_e32 v242, 2, v242
	v_xor_b32_e32 v236, v236, v242
	v_lshlrev_b32_e32 v236, 4, v236
	v_mov_b32_e32 v237, 0
	v_lshrrev_b32_e32 v238, 3, v214
	v_lshl_add_u32 v238, v243, 3, v238
	s_cbranch_scc1 .LBB0_561
	s_lshl_b32 s4, s50, 3
	s_cmp_gt_i32 s50, 7
	s_mov_b64 s[28:29], -1
	s_cbranch_scc0 .LBB0_558
	v_mov_b64_e32 v[2:3], s[22:23]
	v_mad_u64_u32 v[2:3], s[28:29], v214, s73, v[2:3]
	s_mov_b32 s5, s89
	v_lshl_add_u64 v[2:3], s[4:5], 1, v[2:3]
	v_lshl_add_u64 v[2:3], v[2:3], 0, s[92:93]
	s_mov_b64 s[28:29], 0
.LBB0_558:
	s_andn2_b64 vcc, exec, s[28:29]
	s_cbranch_vccnz .LBB0_560
	v_lshlrev_b32_e32 v0, 10, v238
	v_lshl_add_u64 v[2:3], s[26:27], 0, v[0:1]
	s_ashr_i32 s5, s4, 31
	v_lshl_add_u64 v[2:3], v[2:3], 0, v[236:237]

; #define GL(T, p) (*(const __attribute__((address_space(1))) T*)(p))
; template <int DQK, int MODE> __device__ __forceinline__ void unit(const Desc& d, int q0, ATT_LAS char* shm, const float* biasg, float sinkl2) {
;     ...
;     if (MODE == 1) { const int idx = tid - 128; bias_l[tid] = (idx >= 0 && idx <= 256) ? biasg[idx] : NEGBIG; }
;     ATT_DMA(t0, 0);
;     bf16x8 qr[ND0];
;     { const bf16* Qw = d.Q + (size_t)(qw + r32) * d.ldq + hi * 8;
; #pragma unroll
;       for (int d0 = 0; d0 < ND0; ++d0) qr[d0] = GL(bf16x8, Qw + d0 * 16); }
;     float mhat = 0.f, l_reg = 0.f; f32x16 o[2]; o[0] = f32x16{}; o[1] = f32x16{}; f32x16 negm = f32x16{};
;     constexpr bool MSUM = true;
;     f32x16 lacc = f32x16{}; const bf16x8 ones8 = (bf16x8){0x3f80, 0x3f80, 0x3f80, 0x3f80, 0x3f80, 0x3f80, 0x3f80, 0x3f80};
;     const int vb0 = (int)(lds0 + LDS_V) + ((lane >> 4) & 1) * 32 + (lane & 3) * 8 + (4 * hi + ((lane & 15) >> 2)) * 64;
;     int buf = 0;
.LBB0_569:
	s_add_i32 s4, s49, s80
	s_lshl_b32 s4, s4, 8
	s_lshl_b32 s5, s50, 5
	s_add_i32 s28, s5, s4
	s_lshl_b32 s4, s50, 4
	v_lshrrev_b32_e32 v0, 2, v214
	v_and_or_b32 v0, s4, 48, v0
	s_ashr_i32 s4, s36, 3
	s_andn2_b32 s4, s4, 31
	v_lshlrev_b32_e32 v0, 10, v0
	s_ashr_i32 s5, s4, 31
	v_lshlrev_b32_e32 v215, 3, v4
	v_lshl_add_u64 v[2:3], s[26:27], 0, v[0:1]
	s_lshl_b64 s[42:43], s[4:5], 1
	v_and_b32_e32 v5, 24, v215
	v_lshl_add_u64 v[2:3], v[2:3], 0, s[42:43]
	v_lshlrev_b32_e32 v6, 1, v5
	v_mov_b32_e32 v7, v1
	v_lshl_add_u64 v[2:3], v[2:3], 0, v[6:7]
	v_and_b32_e32 v216, 31, v4
	v_lshl_add_u64 v[2:3], v[2:3], 0, s[90:91]
	s_lshl_b32 s29, s50, 10
	v_lshrrev_b32_e32 v217, 5, v214
	s_add_i32 s51, s29, s62
	s_mov_b32 s4, m0
	s_mov_b32 m0, s51
	s_nop 0
	global_load_lds_dwordx4 v[2:3], off
	s_mov_b32 m0, s4
	v_or_b32_e32 v6, s28, v216
	v_mov_b64_e32 v[2:3], s[6:7]
	v_mad_i64_i32 v[2:3], s[4:5], v6, s81, v[2:3]
	v_lshlrev_b32_e32 v208, 4, v217
	v_mov_b32_e32 v209, v1
	v_lshl_add_u64 v[2:3], v[2:3], 0, v[208:209]
	global_load_dwordx4 v[178:181], v[2:3], off
	global_load_dwordx4 v[182:185], v[2:3], off offset:32
	global_load_dwordx4 v[186:189], v[2:3], off offset:64
	global_load_dwordx4 v[190:193], v[2:3], off offset:96
	global_load_dwordx4 v[194:197], v[2:3], off offset:128
	global_load_dwordx4 v[198:201], v[2:3], off offset:160
	s_and_b32 s37, s36, 0x3fffffc0
	s_lshl_b32 s4, s37, 2
	s_add_i32 s54, s4, 0
	s_cmp_gt_i32 s50, 7
	s_cselect_b64 s[36:37], -1, 0
	s_lshl_b32 s60, s50, 3
	s_ashr_i32 s69, s60, 31
	s_mov_b32 s61, s89
	s_cmp_gt_i32 s50, -1
	s_mov_b32 s68, s60
	s_cselect_b64 s[58:59], -1, 0
	s_lshl_b32 s55, s39, 10
	s_lshl_b64 s[60:61], s[60:61], 1
	s_add_u32 s64, s22, s60
	v_lshlrev_b32_e32 v6, 4, v4
	s_addc_u32 s65, s23, s61
	s_lshl_b64 s[60:61], s[88:89], 1
	v_lshlrev_b32_e32 v2, 1, v4
	v_lshlrev_b32_e32 v3, 8, v217
	v_and_b32_e32 v6, 0xc0, v6
	s_add_u32 s74, s22, s60
	v_and_b32_e32 v2, 32, v2
	s_addc_u32 s75, s23, s61
	v_or3_b32 v3, v6, v3, v5
	v_add3_u32 v219, v2, s62, v3
	v_and_b32_e32 v2, 3, v4
	s_add_u32 s42, s11, s42
	v_lshl_or_b32 v0, v2, 4, v0
	s_addc_u32 s43, s46, s43
	v_lshl_add_u64 v[210:211], s[42:43], 0, v[0:1]
	s_lshl_b64 s[42:43], s[68:69], 1
	v_lshlrev_b32_e32 v7, 10, v217
	v_lshlrev_b32_e32 v8, 4, v216
	s_mov_b32 s42, s47
	v_add3_u32 v209, 0, v7, v8
	v_lshrrev_b32_e32 v242, 3, v216
	v_and_b32_e32 v243, 7, v216
	v_bfe_u32 v244, v216, 1, 2
	v_bfe_u32 v245, v216, 4, 1
	v_lshl_or_b32 v244, v245, 2, v244
	v_lshlrev_b32_e32 v242, 10, v242
	v_lshl_add_u32 v242, v243, 7, v242
	v_add_u32_e32 v245, 0, v217
	v_xor_b32_e32 v245, v245, v244
	v_lshl_add_u32 v221, v245, 4, v242
	v_add_u32_e32 v245, 2, v217
	v_xor_b32_e32 v245, v245, v244
	v_lshl_add_u32 v223, v245, 4, v242
	v_add_u32_e32 v245, 4, v217
	v_xor_b32_e32 v245, v245, v244
	v_lshl_add_u32 v252, v245, 4, v242
	v_add_u32_e32 v245, 6, v217
	v_xor_b32_e32 v245, v245, v244
	v_lshl_add_u32 v253, v245, 4, v242
	v_lshlrev_b32_e32 v0, 10, v238
	s_mov_b32 s43, s48
	v_mov_b32_e32 v2, v1
	v_mov_b32_e32 v3, v1
	v_mov_b32_e32 v4, v1
	v_mov_b32_e32 v5, v1
	v_mov_b32_e32 v6, v1
	v_mov_b32_e32 v7, v1
	v_mov_b32_e32 v8, v1
	v_mov_b32_e32 v9, v1
	v_mov_b32_e32 v10, v1
	v_mov_b32_e32 v11, v1
	v_mov_b32_e32 v12, v1
	v_mov_b32_e32 v13, v1
	v_mov_b32_e32 v14, v1
	v_mov_b32_e32 v15, v1
	v_mov_b32_e32 v16, v1
	v_mov_b32_e32 v17, v1
	v_mov_b32_e32 v18, v1
	v_mov_b32_e32 v19, v1
	v_mov_b32_e32 v20, v1
	v_mov_b32_e32 v21, v1
	v_mov_b32_e32 v22, v1
	v_mov_b32_e32 v23, v1
	v_mov_b32_e32 v24, v1
	v_mov_b32_e32 v25, v1
	v_mov_b32_e32 v26, v1
	v_mov_b32_e32 v27, v1
	v_mov_b32_e32 v28, v1
	v_mov_b32_e32 v29, v1
	v_mov_b32_e32 v30, v1
	v_mov_b32_e32 v31, v1
	v_lshl_add_u64 v[212:213], s[42:43], 0, v[0:1]
	v_lshl_add_u64 v[212:213], v[212:213], 0, v[236:237]
	v_mov_b32_e32 v0, v1
	v_mov_b32_e32 v220, 0
	v_mov_b64_e32 v[32:33], v[30:31]
	v_cmp_gt_u32_e64 s[4:5], 32, v214
	v_lshl_add_u32 v218, v216, 2, s54
	s_mov_b32 s60, 0
	v_mov_b32_e32 v82, v1
	v_mov_b32_e32 v83, v1
	v_mov_b32_e32 v84, v1
	v_mov_b32_e32 v85, v1
	v_mov_b32_e32 v86, v1
	v_mov_b32_e32 v87, v1
	v_mov_b32_e32 v88, v1
	v_mov_b32_e32 v89, v1
	v_mov_b32_e32 v90, v1
	v_mov_b32_e32 v91, v1
	v_mov_b32_e32 v92, v1
	v_mov_b32_e32 v93, v1
	v_mov_b32_e32 v94, v1
	v_mov_b32_e32 v95, v1
	v_mov_b32_e32 v96, v1
	v_mov_b32_e32 v97, v1
	s_mov_b64 s[96:97], 0
	s_mov_b32 s61, 0
	v_mov_b64_e32 v[30:31], v[28:29]
	v_mov_b64_e32 v[28:29], v[26:27]
	v_mov_b64_e32 v[26:27], v[24:25]
	v_mov_b64_e32 v[24:25], v[22:23]
	v_mov_b64_e32 v[22:23], v[20:21]
	v_mov_b64_e32 v[20:21], v[18:19]
	v_mov_b64_e32 v[18:19], v[16:17]
	v_mov_b64_e32 v[16:17], v[14:15]
	v_mov_b64_e32 v[14:15], v[12:13]
	v_mov_b64_e32 v[12:13], v[10:11]
	v_mov_b64_e32 v[10:11], v[8:9]
	v_mov_b64_e32 v[8:9], v[6:7]
	v_mov_b64_e32 v[6:7], v[4:5]
	v_mov_b64_e32 v[4:5], v[2:3]
	v_mov_b64_e32 v[2:3], v[0:1]
	v_mov_b32_e32 v66, 0
	v_mov_b32_e32 v67, v220
	v_mov_b32_e32 v68, v220
	v_mov_b32_e32 v69, v220
	v_mov_b32_e32 v70, v220
	v_mov_b32_e32 v71, v220
	v_mov_b32_e32 v72, v220
	v_mov_b32_e32 v73, v220
	v_mov_b32_e32 v74, v220
	v_mov_b32_e32 v75, v220
	v_mov_b32_e32 v76, v220
	v_mov_b32_e32 v77, v220
	v_mov_b32_e32 v78, v220
	v_mov_b32_e32 v79, v220
	v_mov_b32_e32 v80, v220
	v_mov_b32_e32 v81, v220
	s_branch .LBB0_572

; #define ATT_LAS __attribute__((address_space(3)))
; __device__ __forceinline__ void pv(f32x16* o, int vb, bf16x8 pa0, bf16x8 pa1, bf16x8 pa2, bf16x8 pa3) {
;     ...
;             asm volatile("ds_read_b64_tr_b16 %0,%1 offset:%c2" : "=&v"(lo[ks]) : "v"(vb), "i"(d0 * 4096 + ks * 1024) : "memory");
;             asm volatile("ds_read_b64_tr_b16 %0,%1 offset:%c2" : "=&v"(hi[ks]) : "v"(vb), "i"(d0 * 4096 + ks * 1024 + 512) : "memory"); }
; template <int DQK, int MODE> __device__ __forceinline__ void unit(const Desc& d, int q0, ATT_LAS char* shm, const float* biasg, float sinkl2) {
;     ...
;             { const ATT_LAS char* kb = shm + LDS_K + buf * KSLOT + hi * 1024 + r32 * 16;
; #pragma unroll
;               for (int d0 = 0; d0 < ND0; ++d0) {
;                   const bf16x8 b0 = *(const ATT_LAS bf16x8*)(kb + d0 * 2048);
;                   const bf16x8 b1 = *(const ATT_LAS bf16x8*)(kb + d0 * 2048 + 512);
;                   if (d0 == 0) { p0 = __builtin_amdgcn_mfma_f32_32x32x16_bf16(b0, qr[0], negm, 0, 0, 0); p1 = __builtin_amdgcn_mfma_f32_32x32x16_bf16(b1, qr[0], negm, 0, 0, 0); }
;                   else { p0 = __builtin_amdgcn_mfma_f32_32x32x16_bf16(b0, qr[d0], p0, 0, 0, 0); p1 = __builtin_amdgcn_mfma_f32_32x32x16_bf16(b1, qr[d0], p1, 0, 0, 0); } } }
.LBB0_586:
	s_mul_i32 s39, s60, 0x3000
	v_add_u32_e32 v0, s39, v209
	v_add_u32_e32 v234, s39, v221
	v_add_u32_e32 v235, s39, v223
	v_add_u32_e32 v236, s39, v252
	v_add_u32_e32 v237, s39, v253
	ds_read_b128 v[130:133], v234
	ds_read_b128 v[134:137], v234 offset:4096
	ds_read_b128 v[138:141], v235
	ds_read_b128 v[142:145], v235 offset:4096
	ds_read_b128 v[146:149], v236
	ds_read_b128 v[150:153], v236 offset:4096
	ds_read_b128 v[154:157], v237
	ds_read_b128 v[158:161], v237 offset:4096
	ds_read_b128 v[162:165], v0 offset:8192
	ds_read_b128 v[166:169], v0 offset:8704
	ds_read_b128 v[170:173], v0 offset:10240
	ds_read_b128 v[174:177], v0 offset:10752
	v_mov_b32_e32 v224, s40
	v_mov_b32_e32 v225, s40
	v_mov_b32_e32 v226, s40
	v_mov_b32_e32 v227, s40
	v_lshl_add_u32 v0, s60, 13, v219
	s_waitcnt lgkmcnt(11)
	v_mfma_f32_32x32x16_bf16 v[114:129], v[130:133], v[178:181], v[66:81]
	ds_read_b64_tr_b16 v[34:35], v0
	s_waitcnt lgkmcnt(11)
	v_mfma_f32_32x32x16_bf16 v[98:113], v[134:137], v[178:181], v[66:81]
	ds_read_b64_tr_b16 v[36:37], v0 offset:512
	s_waitcnt lgkmcnt(11)
	v_mfma_f32_32x32x16_bf16 v[114:129], v[138:141], v[182:185], v[114:129]
	ds_read_b64_tr_b16 v[38:39], v0 offset:1024
	s_waitcnt lgkmcnt(11)
	v_mfma_f32_32x32x16_bf16 v[98:113], v[142:145], v[182:185], v[98:113]
	ds_read_b64_tr_b16 v[40:41], v0 offset:1536
	s_waitcnt lgkmcnt(11)
	v_mfma_f32_32x32x16_bf16 v[114:129], v[146:149], v[186:189], v[114:129]
	ds_read_b64_tr_b16 v[42:43], v0 offset:2048
	s_waitcnt lgkmcnt(11)
	v_mfma_f32_32x32x16_bf16 v[98:113], v[150:153], v[186:189], v[98:113]
	ds_read_b64_tr_b16 v[44:45], v0 offset:2560
	s_waitcnt lgkmcnt(11)
	v_mfma_f32_32x32x16_bf16 v[114:129], v[154:157], v[190:193], v[114:129]
	ds_read_b64_tr_b16 v[46:47], v0 offset:3072
	s_waitcnt lgkmcnt(11)
	v_mfma_f32_32x32x16_bf16 v[98:113], v[158:161], v[190:193], v[98:113]
	ds_read_b64_tr_b16 v[48:49], v0 offset:3584
	s_waitcnt lgkmcnt(11)
	v_mfma_f32_32x32x16_bf16 v[114:129], v[162:165], v[194:197], v[114:129]
	ds_read_b64_tr_b16 v[50:51], v0 offset:4096
	s_waitcnt lgkmcnt(11)
	v_mfma_f32_32x32x16_bf16 v[98:113], v[166:169], v[194:197], v[98:113]
	ds_read_b64_tr_b16 v[52:53], v0 offset:4608
	s_waitcnt lgkmcnt(11)
	v_mfma_f32_32x32x16_bf16 v[114:129], v[170:173], v[198:201], v[114:129]
	ds_read_b64_tr_b16 v[54:55], v0 offset:5120
	s_waitcnt lgkmcnt(11)
	v_mfma_f32_32x32x16_bf16 v[98:113], v[174:177], v[198:201], v[98:113]
	ds_read_b64_tr_b16 v[56:57], v0 offset:5632
	ds_read_b64_tr_b16 v[58:59], v0 offset:6144
	ds_read_b64_tr_b16 v[60:61], v0 offset:6656
	ds_read_b64_tr_b16 v[62:63], v0 offset:7168
	ds_read_b64_tr_b16 v[64:65], v0 offset:7680
	s_nop 15
	s_nop 7
	s_nop 0
	v_max3_f32 v0, v114, v115, v98
	v_max3_f32 v222, v116, v117, v99
	s_nop 0
	v_max3_f32 v0, v0, v100, v101
	v_max3_f32 v222, v222, v120, v121
	s_nop 0
	v_max3_f32 v0, v0, v118, v119
	v_max3_f32 v222, v222, v104, v105
	s_nop 0
	v_max3_f32 v0, v0, v102, v103
	v_max3_f32 v222, v222, v124, v125
	s_nop 0
	v_max3_f32 v0, v0, v122, v123
	v_max3_f32 v222, v222, v108, v109
	s_nop 0
	v_max3_f32 v0, v0, v106, v107
	v_max3_f32 v222, v222, v128, v129
	s_nop 0
	v_max3_f32 v0, v0, v126, v127
	v_max3_f32 v222, v222, v112, v113
	s_nop 0
	v_max3_f32 v0, v0, v110, v111
	s_nop 0
	v_max_f32_e32 v0, v0, v222
	s_nop 0
	v_mov_b32_e32 v222, v0
	s_nop 1
	v_permlane32_swap_b32_e32 v0, v222
	v_max_f32_e32 v0, v0, v222
	s_cmp_lg_u32 s96, 0
	s_cbranch_scc0 .LBB0_591
	v_cmp_lt_f32_e32 vcc, s70, v0
	s_cbranch_vccz .LBB0_571
	v_max_f32_e32 v250, v0, v0
	v_max_f32_e32 v250, 0, v250
	s_and_saveexec_b64 s[42:43], s[4:5]
	v_exp_f32_e64 v251, -v250
	s_nop 0
	ds_write_b32 v218, v251 offset:40960
	s_or_b64 exec, exec, s[42:43]
	s_waitcnt lgkmcnt(0)
	v_add_u32_e32 v251, s54, v208
	ds_read_b128 v[234:237], v251 offset:40960
	ds_read_b128 v[238:241], v251 offset:40992
	ds_read_b128 v[242:245], v251 offset:41024
	ds_read_b128 v[246:249], v251 offset:41056
	v_add_f32_e32 v220, v220, v250
	v_xor_b32_e32 v81, 0x80000000, v220
	v_sub_f32_e32 v114, v114, v250
	v_sub_f32_e32 v115, v115, v250
	v_sub_f32_e32 v116, v116, v250
	v_sub_f32_e32 v117, v117, v250
	v_sub_f32_e32 v118, v118, v250
	v_sub_f32_e32 v119, v119, v250
	v_sub_f32_e32 v120, v120, v250
	v_sub_f32_e32 v121, v121, v250
	v_sub_f32_e32 v122, v122, v250
	v_sub_f32_e32 v123, v123, v250
	v_sub_f32_e32 v124, v124, v250
	v_sub_f32_e32 v125, v125, v250
	v_sub_f32_e32 v126, v126, v250
	v_sub_f32_e32 v127, v127, v250
	v_sub_f32_e32 v128, v128, v250
	v_sub_f32_e32 v129, v129, v250
	v_sub_f32_e32 v98, v98, v250
	v_sub_f32_e32 v99, v99, v250
	v_sub_f32_e32 v100, v100, v250
	v_sub_f32_e32 v101, v101, v250
	v_sub_f32_e32 v102, v102, v250
	v_sub_f32_e32 v103, v103, v250
	v_sub_f32_e32 v104, v104, v250
	v_sub_f32_e32 v105, v105, v250
	v_sub_f32_e32 v106, v106, v250
	v_sub_f32_e32 v107, v107, v250
	v_sub_f32_e32 v108, v108, v250
	v_sub_f32_e32 v109, v109, v250
	v_sub_f32_e32 v110, v110, v250
	v_sub_f32_e32 v111, v111, v250
	v_sub_f32_e32 v112, v112, v250
	v_sub_f32_e32 v113, v113, v250
	s_waitcnt lgkmcnt(0)
	v_pk_mul_f32 v[2:3], v[2:3], v[234:235]
	v_pk_mul_f32 v[4:5], v[4:5], v[236:237]
	v_pk_mul_f32 v[6:7], v[6:7], v[238:239]
	v_pk_mul_f32 v[8:9], v[8:9], v[240:241]
	v_pk_mul_f32 v[10:11], v[10:11], v[242:243]
	v_pk_mul_f32 v[12:13], v[12:13], v[244:245]
	v_pk_mul_f32 v[14:15], v[14:15], v[246:247]
	v_pk_mul_f32 v[16:17], v[16:17], v[248:249]
	v_pk_mul_f32 v[18:19], v[18:19], v[234:235]
	v_pk_mul_f32 v[20:21], v[20:21], v[236:237]
	v_pk_mul_f32 v[22:23], v[22:23], v[238:239]
	v_pk_mul_f32 v[24:25], v[24:25], v[240:241]
	v_pk_mul_f32 v[26:27], v[26:27], v[242:243]
	v_pk_mul_f32 v[28:29], v[28:29], v[244:245]
	v_pk_mul_f32 v[30:31], v[30:31], v[246:247]
	v_pk_mul_f32 v[32:33], v[32:33], v[248:249]
	v_pk_mul_f32 v[82:83], v[82:83], v[234:235]
	v_pk_mul_f32 v[84:85], v[84:85], v[236:237]
	v_pk_mul_f32 v[86:87], v[86:87], v[238:239]
	v_pk_mul_f32 v[88:89], v[88:89], v[240:241]
	v_pk_mul_f32 v[90:91], v[90:91], v[242:243]
	v_pk_mul_f32 v[92:93], v[92:93], v[244:245]
	v_pk_mul_f32 v[94:95], v[94:95], v[246:247]
	v_pk_mul_f32 v[96:97], v[96:97], v[248:249]
	v_mov_b32_e32 v80, v81
	v_mov_b32_e32 v79, v81
	v_mov_b32_e32 v78, v81
	v_mov_b32_e32 v77, v81
	v_mov_b32_e32 v76, v81
	v_mov_b32_e32 v75, v81
	v_mov_b32_e32 v74, v81
	v_mov_b32_e32 v73, v81
	v_mov_b32_e32 v72, v81
	v_mov_b32_e32 v71, v81
	v_mov_b32_e32 v70, v81
	v_mov_b32_e32 v69, v81
	v_mov_b32_e32 v68, v81
	v_mov_b32_e32 v67, v81
	v_mov_b32_e32 v66, v81
	s_branch .LBB0_571
